# FFN-up0 idle-round pool-weight fold: the wave-uniform weights staged once in LDS and broadcast from there instead of 32 broadcast vector loads per step
# speedup vs baseline: 1.0217x; 1.0147x over previous
; template <int PART>
; __device__ __forceinline__ void phase_prologue_late(const Params& p, LAS unsigned char* lds, int cu0) {
;     ...
;         for (int it = gw; it < 1024; it += NGW) {
;             const int g = it >> 8, cb = (it >> 4) & 15, nb2 = it & 15, n = nb2 * 64 + lane;
;             float acc[8];
; #pragma unroll
;             for (int i = 0; i < 8; ++i) acc[i] = 0.f;
;             const float* wp = Wp + ((size_t)g * 128 + cb * 8) * 128;
;             for (int d0 = 0; d0 < 128; d0 += 16) {
;                 float wv[16];
; #pragma unroll
;                 for (int dd = 0; dd < 16; ++dd) wv[dd] = Wo[(size_t)(g * 128 + d0 + dd) * D + n];
; #pragma unroll
;                 for (int dd = 0; dd < 16; ++dd) { const float w = wv[dd] * sc[g * 128 + d0 + dd];
; #pragma unroll
;                     for (int i = 0; i < 8; ++i) acc[i] += wp[i * 128 + d0 + dd] * w; }
;             }
.LBB0_510:
	s_lshl_b32 s4, s15, 2
	s_ashr_i32 s18, s9, 8
	s_and_b32 s4, s4, 0xf00
	s_lshl_b32 s22, s18, 7
	v_lshl_or_b32 v24, v41, 2, s4
	s_lshl_b32 s4, s9, 8
	s_ashr_i32 s19, s18, 31
	s_ashr_i32 s23, s22, 31
	s_and_b32 s4, s4, 0xf000
	s_lshl_b64 s[20:21], s[18:19], 16
	s_lshl_b64 s[18:19], s[22:23], 12
	s_add_u32 s18, s13, s18
	v_readlane_b32 s52, v254, 21
	s_addc_u32 s19, s14, s19
	v_readlane_b32 s66, v254, 35
	v_readlane_b32 s67, v254, 36
	v_lshl_add_u64 v[26:27], s[18:19], 0, v[24:25]
	s_or_b32 s4, s20, s4
	s_mov_b64 s[18:19], s[66:67]
	v_readlane_b32 s53, v254, 22
	v_readlane_b32 s54, v254, 23
	v_readlane_b32 s55, v254, 24
	v_readlane_b32 s56, v254, 25
	v_readlane_b32 s57, v254, 26
	v_readlane_b32 s58, v254, 27
	v_readlane_b32 s59, v254, 28
	v_readlane_b32 s60, v254, 29
	v_readlane_b32 s61, v254, 30
	v_readlane_b32 s62, v254, 31
	v_readlane_b32 s63, v254, 32
	v_readlane_b32 s64, v254, 33
	v_readlane_b32 s65, v254, 34
	s_add_u32 s4, s18, s4
	s_addc_u32 s17, s19, s21
	s_lshl_b64 s[18:19], s[22:23], 2
	v_readlane_b32 s52, v254, 5
	v_readlane_b32 s53, v254, 6
	s_add_u32 s18, s52, s18
	s_addc_u32 s19, s53, s19
	s_mov_b32 s20, -16
	s_mov_b64 s[38:39], 0
	v_mov_b32_e32 v28, 0
	v_mov_b32_e32 v29, v25
	v_mov_b32_e32 v34, 0
	v_mov_b32_e32 v35, v25
	v_mov_b32_e32 v32, 0
	v_mov_b32_e32 v33, v25
	v_mov_b32_e32 v30, 0
	v_mov_b32_e32 v31, v25
	v_readlane_b32 s54, v254, 7
	v_readlane_b32 s55, v254, 8
	v_readlane_b32 s56, v254, 9
	v_readlane_b32 s57, v254, 10
	v_readlane_b32 s58, v254, 11
	v_readlane_b32 s59, v254, 12
	v_readlane_b32 s60, v254, 13
	v_readlane_b32 s61, v254, 14
	v_readlane_b32 s62, v254, 15
	v_readlane_b32 s63, v254, 16
	v_readlane_b32 s64, v254, 17
	v_readlane_b32 s65, v254, 18
	v_readlane_b32 s66, v254, 19
	v_readlane_b32 s67, v254, 20
	s_mov_b32 s42, s4
	s_mov_b32 s43, s17
	v_lshlrev_b32_e32 v178, 4, v41
	global_load_dwordx4 v[180:183], v178, s[42:43]
	global_load_dwordx4 v[184:187], v178, s[42:43] offset:1024
	global_load_dwordx4 v[188:191], v178, s[42:43] offset:2048
	global_load_dwordx4 v[192:195], v178, s[42:43] offset:3072
	v_lshrrev_b32_e32 v177, 6, v40
	v_mul_u32_u24_e32 v177, 0x4100, v177
	v_add_u32_e32 v179, v177, v178
	s_waitcnt vmcnt(0)
	ds_write_b128 v179, v[180:183]
	ds_write_b128 v179, v[184:187] offset:1024
	ds_write_b128 v179, v[188:191] offset:2048
	ds_write_b128 v179, v[192:195] offset:3072
	s_waitcnt lgkmcnt(0)
.LBB0_511:
	v_add_u32_e32 v196, s38, v177
	v_add_co_u32_e32 v0, vcc, 0xffff1000, v26
	s_add_u32 s24, s18, s38
	s_nop 0
	v_addc_co_u32_e32 v1, vcc, -1, v27, vcc
	v_add_co_u32_e32 v16, vcc, 0xffff2000, v26
	s_addc_u32 s25, s19, s39
	s_nop 0
	v_addc_co_u32_e32 v17, vcc, -1, v27, vcc
	v_add_co_u32_e32 v18, vcc, 0xffff3000, v26
	s_add_u32 s42, s4, s38
	s_nop 0
	v_addc_co_u32_e32 v19, vcc, -1, v27, vcc
	v_add_co_u32_e32 v38, vcc, 0xffff4000, v26
	s_addc_u32 s43, s17, s39
	s_nop 0
	v_addc_co_u32_e32 v39, vcc, -1, v27, vcc
	v_add_co_u32_e32 v162, vcc, 0xffff5000, v26
	global_load_dword v36, v[26:27], off offset:-4096
	global_load_dword v37, v[26:27], off
	v_addc_co_u32_e32 v163, vcc, -1, v27, vcc
	global_load_dword v24, v[0:1], off
	s_nop 0
	global_load_dwordx4 v[0:3], v25, s[24:25] offset:48
	global_load_dwordx4 v[4:7], v25, s[24:25] offset:32
	global_load_dwordx4 v[12:15], v25, s[24:25]
	global_load_dwordx4 v[8:11], v25, s[24:25] offset:16
	global_load_dword v172, v[16:17], off
	global_load_dword v173, v[18:19], off
	ds_read_b128 v[42:45], v196 offset:48
	ds_read_b128 v[46:49], v196 offset:32
	ds_read_b128 v[50:53], v196 offset:16
	ds_read_b128 v[54:57], v196
	s_nop 0
	ds_read_b128 v[16:19], v196 offset:560
	ds_read_b128 v[58:61], v196 offset:544
	ds_read_b128 v[62:65], v196 offset:528
	ds_read_b128 v[66:69], v196 offset:512
	ds_read_b128 v[70:73], v196 offset:1072
	ds_read_b128 v[74:77], v196 offset:1056
	ds_read_b128 v[78:81], v196 offset:1040
	ds_read_b128 v[82:85], v196 offset:1024
	ds_read_b128 v[20:23], v196 offset:1584
	ds_read_b128 v[86:89], v196 offset:1568
	ds_read_b128 v[90:93], v196 offset:1552
	ds_read_b128 v[94:97], v196 offset:1536
	ds_read_b128 v[98:101], v196 offset:2096
	ds_read_b128 v[102:105], v196 offset:2080
	ds_read_b128 v[106:109], v196 offset:2064
	ds_read_b128 v[110:113], v196 offset:2048
	ds_read_b128 v[114:117], v196 offset:2608
	ds_read_b128 v[118:121], v196 offset:2592
	ds_read_b128 v[122:125], v196 offset:2576
	ds_read_b128 v[126:129], v196 offset:2560
	ds_read_b128 v[130:133], v196 offset:3120
	ds_read_b128 v[134:137], v196 offset:3104
	ds_read_b128 v[138:141], v196 offset:3088
	ds_read_b128 v[142:145], v196 offset:3072
	ds_read_b128 v[146:149], v196 offset:3632
	ds_read_b128 v[150:153], v196 offset:3616
	ds_read_b128 v[154:157], v196 offset:3600
	ds_read_b128 v[158:161], v196 offset:3584
	global_load_dword v176, v[38:39], off
	v_add_co_u32_e32 v38, vcc, 0xffff6000, v26
	s_add_i32 s20, s20, 16
	s_nop 0
	v_addc_co_u32_e32 v39, vcc, -1, v27, vcc
	v_add_co_u32_e32 v164, vcc, 0xffff7000, v26
	global_load_dword v162, v[162:163], off
	s_nop 0
	global_load_dword v163, v[38:39], off
	v_addc_co_u32_e32 v165, vcc, -1, v27, vcc
	v_add_co_u32_e32 v38, vcc, 0xffff8000, v26
	s_add_u32 s38, s38, 64
	s_nop 0
	v_addc_co_u32_e32 v39, vcc, -1, v27, vcc
	v_add_co_u32_e32 v166, vcc, 0xffff9000, v26
	global_load_dword v164, v[164:165], off
	s_nop 0
	global_load_dword v165, v[38:39], off
	v_addc_co_u32_e32 v167, vcc, -1, v27, vcc
	v_add_co_u32_e32 v38, vcc, 0xffffa000, v26
	s_addc_u32 s39, s39, 0
	s_nop 0
	v_addc_co_u32_e32 v39, vcc, -1, v27, vcc
	v_add_co_u32_e32 v168, vcc, 0xffffb000, v26
	global_load_dword v166, v[166:167], off
	s_nop 0
	global_load_dword v167, v[38:39], off
	v_addc_co_u32_e32 v169, vcc, -1, v27, vcc
	v_add_co_u32_e32 v38, vcc, 0xffffc000, v26
	s_cmpk_lt_u32 s20, 0x70
	s_nop 0
	v_addc_co_u32_e32 v39, vcc, -1, v27, vcc
	v_add_co_u32_e32 v170, vcc, 0xffffd000, v26
	global_load_dword v168, v[168:169], off
	s_nop 0
	global_load_dword v169, v[38:39], off
	v_addc_co_u32_e32 v171, vcc, -1, v27, vcc
	v_add_co_u32_e32 v38, vcc, 0xffffe000, v26
	s_waitcnt vmcnt(14)
; template <int PART>
; __device__ __forceinline__ void phase_prologue_late(const Params& p, LAS unsigned char* lds, int cu0) {
;     ...
;             for (int d0 = 0; d0 < 128; d0 += 16) {
;                 float wv[16];
; #pragma unroll
;                 for (int dd = 0; dd < 16; ++dd) wv[dd] = Wo[(size_t)(g * 128 + d0 + dd) * D + n];
; #pragma unroll
;                 for (int dd = 0; dd < 16; ++dd) { const float w = wv[dd] * sc[g * 128 + d0 + dd];
; #pragma unroll
;                     for (int i = 0; i < 8; ++i) acc[i] += wp[i * 128 + d0 + dd] * w; }
	v_pk_mul_f32 v[2:3], v[36:37], v[2:3]
	v_addc_co_u32_e32 v39, vcc, -1, v27, vcc
	global_load_dword v170, v[170:171], off
	s_nop 0
	global_load_dword v171, v[38:39], off
	s_waitcnt vmcnt(14)
	v_mul_f32_e32 v12, v24, v12
	s_waitcnt vmcnt(12)
	v_mul_f32_e32 v24, v172, v13
	s_waitcnt vmcnt(11)
	v_mul_f32_e32 v14, v173, v14
	s_waitcnt vmcnt(11) lgkmcnt(0)
	v_mov_b32_e32 v36, v54
	s_waitcnt vmcnt(11) lgkmcnt(0)
	v_mov_b32_e32 v37, v66
	v_mov_b32_e32 v38, v56
	v_mov_b32_e32 v39, v68
	v_mov_b32_e32 v68, v57
	s_waitcnt vmcnt(11) lgkmcnt(0)
	v_mov_b32_e32 v56, v82
	s_waitcnt vmcnt(11) lgkmcnt(0)
	v_mov_b32_e32 v57, v94
	s_waitcnt vmcnt(11) lgkmcnt(12)
	v_mov_b32_e32 v172, v110
	s_waitcnt vmcnt(11) lgkmcnt(8)
	v_mov_b32_e32 v173, v126
	v_mov_b32_e32 v66, v55
	v_mov_b32_e32 v94, v83
	v_mov_b32_e32 v126, v111
	s_waitcnt vmcnt(11) lgkmcnt(4)
	v_mov_b32_e32 v174, v142
	s_waitcnt vmcnt(11) lgkmcnt(0)
	v_mov_b32_e32 v175, v158
	v_pk_fma_f32 v[34:35], v[12:13], v[36:37], v[34:35] op_sel_hi:[0,1,1]
	v_pk_fma_f32 v[32:33], v[12:13], v[56:57], v[32:33] op_sel_hi:[0,1,1]
	v_pk_fma_f32 v[30:31], v[12:13], v[172:173], v[30:31] op_sel_hi:[0,1,1]
	v_mov_b32_e32 v82, v84
	v_mov_b32_e32 v83, v96
	v_mov_b32_e32 v110, v112
	v_mov_b32_e32 v111, v128
	v_mov_b32_e32 v158, v143
	v_pk_fma_f32 v[12:13], v[12:13], v[174:175], v[28:29] op_sel_hi:[0,1,1]
	v_pk_fma_f32 v[28:29], v[24:25], v[66:67], v[34:35] op_sel_hi:[0,1,1]
	v_pk_fma_f32 v[32:33], v[24:25], v[94:95], v[32:33] op_sel_hi:[0,1,1]
	v_pk_fma_f32 v[30:31], v[24:25], v[126:127], v[30:31] op_sel_hi:[0,1,1]
	v_mov_b32_e32 v54, v50
	v_mov_b32_e32 v96, v85
	v_mov_b32_e32 v128, v113
	v_mov_b32_e32 v142, v144
	v_mov_b32_e32 v143, v160
	v_mul_f32_e32 v50, v2, v132
	s_waitcnt vmcnt(10) lgkmcnt(0)
	v_mul_f32_e32 v132, v176, v15
	v_pk_fma_f32 v[12:13], v[24:25], v[158:159], v[12:13] op_sel_hi:[0,1,1]
	s_waitcnt vmcnt(8) lgkmcnt(0)
	v_pk_mul_f32 v[8:9], v[162:163], v[8:9]
	v_pk_fma_f32 v[28:29], v[14:15], v[38:39], v[28:29] op_sel_hi:[0,1,1]
	v_pk_fma_f32 v[32:33], v[14:15], v[82:83], v[32:33] op_sel_hi:[0,1,1]
	v_pk_fma_f32 v[30:31], v[14:15], v[110:111], v[30:31] op_sel_hi:[0,1,1]
	v_mov_b32_e32 v55, v62
	v_mov_b32_e32 v84, v78
	v_mov_b32_e32 v85, v90
	v_mov_b32_e32 v112, v106
	v_mov_b32_e32 v113, v122
	v_mov_b32_e32 v160, v145
	v_pk_fma_f32 v[12:13], v[14:15], v[142:143], v[12:13] op_sel_hi:[0,1,1]
	v_pk_fma_f32 v[14:15], v[132:133], v[68:69], v[28:29] op_sel_hi:[0,1,1]
	v_pk_fma_f32 v[28:29], v[132:133], v[96:97], v[32:33] op_sel_hi:[0,1,1]
	v_pk_fma_f32 v[30:31], v[132:133], v[128:129], v[30:31] op_sel_hi:[0,1,1]
	v_pk_mul_f32 v[34:35], v[8:9], v[154:155]
	v_mov_b32_e32 v62, v51
	v_mov_b32_e32 v90, v79
	v_mov_b32_e32 v122, v107
	v_mul_f32_e32 v32, v8, v138
	v_pk_fma_f32 v[12:13], v[132:133], v[160:161], v[12:13] op_sel_hi:[0,1,1]
	v_pk_fma_f32 v[14:15], v[8:9], v[54:55], v[14:15] op_sel_hi:[0,1,1]
	v_pk_fma_f32 v[28:29], v[8:9], v[84:85], v[28:29] op_sel_hi:[0,1,1]
	v_pk_fma_f32 v[30:31], v[8:9], v[112:113], v[30:31] op_sel_hi:[0,1,1]
	v_mov_b32_e32 v33, v34
	s_waitcnt vmcnt(6) lgkmcnt(0)
	v_pk_mul_f32 v[10:11], v[164:165], v[10:11]
	v_mov_b32_e32 v106, v52
	v_mov_b32_e32 v107, v64
	v_mov_b32_e32 v64, v53
	v_mov_b32_e32 v52, v46
	v_mov_b32_e32 v53, v58
	v_mov_b32_e32 v58, v47
	v_mov_b32_e32 v46, v48
	v_mov_b32_e32 v47, v60
	v_mov_b32_e32 v60, v49
	v_mov_b32_e32 v48, v42
	v_mov_b32_e32 v49, v16
	v_mov_b32_e32 v16, v43
	v_mov_b32_e32 v42, v44
	v_mov_b32_e32 v43, v18
	v_mov_b32_e32 v18, v45
	v_mov_b32_e32 v44, v80
	v_mov_b32_e32 v45, v92
	v_mov_b32_e32 v92, v81
	v_mov_b32_e32 v80, v74
	v_mov_b32_e32 v81, v86
	v_mov_b32_e32 v86, v75
	v_mov_b32_e32 v74, v76
	v_mov_b32_e32 v75, v88
	v_mov_b32_e32 v88, v77
	v_mov_b32_e32 v76, v70
	v_mov_b32_e32 v77, v20
	v_mov_b32_e32 v20, v71
	v_mov_b32_e32 v70, v72
	v_mov_b32_e32 v71, v22
	v_mov_b32_e32 v22, v73
	v_mov_b32_e32 v72, v108
	v_mov_b32_e32 v73, v124
	v_mul_f32_e32 v34, v9, v139
	v_pk_add_f32 v[12:13], v[12:13], v[32:33]
	v_pk_mul_f32 v[36:37], v[10:11], v[156:157]
	v_pk_fma_f32 v[14:15], v[8:9], v[62:63], v[14:15] op_sel:[1,0,0]
	v_pk_fma_f32 v[28:29], v[8:9], v[90:91], v[28:29] op_sel:[1,0,0]
	v_pk_fma_f32 v[8:9], v[8:9], v[122:123], v[30:31] op_sel:[1,0,0]
	v_mov_b32_e32 v124, v109
	v_mul_f32_e32 v32, v10, v140
	s_waitcnt vmcnt(4) lgkmcnt(0)
; __device__ __forceinline__ v4u pack8(const float (&f)[8]) { v4u w; w.x = pk2(f[0], f[1]); w.y = pk2(f[2], f[3]); w.z = pk2(f[4], f[5]); w.w = pk2(f[6], f[7]); return w; }
; template <int PART>
; __device__ __forceinline__ void phase_prologue_late(const Params& p, LAS unsigned char* lds, int cu0) {
;     ...
;                 for (int dd = 0; dd < 16; ++dd) { const float w = wv[dd] * sc[g * 128 + d0 + dd];
; #pragma unroll
;                     for (int i = 0; i < 8; ++i) acc[i] += wp[i * 128 + d0 + dd] * w; }
;             }
;             *(v4u*)(WT + (size_t)n * D + g * 128 + cb * 8) = pack8(acc);
;         }
	v_pk_mul_f32 v[4:5], v[166:167], v[4:5]
	v_pk_fma_f32 v[14:15], v[10:11], v[106:107], v[14:15] op_sel_hi:[0,1,1]
	v_pk_fma_f32 v[28:29], v[10:11], v[44:45], v[28:29] op_sel_hi:[0,1,1]
	v_pk_fma_f32 v[8:9], v[10:11], v[72:73], v[8:9] op_sel_hi:[0,1,1]
	v_pk_add_f32 v[12:13], v[12:13], v[34:35]
	v_mov_b32_e32 v33, v36
	v_mov_b32_e32 v108, v102
	v_mov_b32_e32 v109, v118
	v_mul_f32_e32 v38, v11, v141
	v_mov_b32_e32 v39, v37
	v_pk_mul_f32 v[34:35], v[4:5], v[150:151]
	v_pk_fma_f32 v[14:15], v[10:11], v[64:65], v[14:15] op_sel:[1,0,0]
	v_pk_fma_f32 v[28:29], v[10:11], v[92:93], v[28:29] op_sel:[1,0,0]
	v_pk_fma_f32 v[8:9], v[10:11], v[124:125], v[8:9] op_sel:[1,0,0]
	v_pk_add_f32 v[10:11], v[12:13], v[32:33]
	v_mov_b32_e32 v118, v103
	v_mul_f32_e32 v30, v4, v134
	s_waitcnt vmcnt(2) lgkmcnt(0)
	v_pk_mul_f32 v[6:7], v[168:169], v[6:7]
	v_pk_fma_f32 v[12:13], v[4:5], v[52:53], v[14:15] op_sel_hi:[0,1,1]
	v_pk_fma_f32 v[14:15], v[4:5], v[80:81], v[28:29] op_sel_hi:[0,1,1]
	v_pk_fma_f32 v[8:9], v[4:5], v[108:109], v[8:9] op_sel_hi:[0,1,1]
	v_pk_add_f32 v[10:11], v[10:11], v[38:39]
	v_mov_b32_e32 v31, v34
	v_mov_b32_e32 v102, v104
	v_mov_b32_e32 v103, v120
	v_mul_f32_e32 v36, v5, v135
	v_mov_b32_e32 v37, v35
	v_pk_mul_f32 v[32:33], v[6:7], v[152:153]
	v_pk_fma_f32 v[12:13], v[4:5], v[58:59], v[12:13] op_sel:[1,0,0]
	v_pk_fma_f32 v[14:15], v[4:5], v[86:87], v[14:15] op_sel:[1,0,0]
	v_pk_fma_f32 v[4:5], v[4:5], v[118:119], v[8:9] op_sel:[1,0,0]
	v_pk_add_f32 v[8:9], v[10:11], v[30:31]
	v_mov_b32_e32 v120, v105
	v_mul_f32_e32 v28, v6, v136
	s_waitcnt vmcnt(0) lgkmcnt(0)
	v_pk_mul_f32 v[0:1], v[170:171], v[0:1]
	v_pk_fma_f32 v[10:11], v[6:7], v[46:47], v[12:13] op_sel_hi:[0,1,1]
	v_pk_fma_f32 v[12:13], v[6:7], v[74:75], v[14:15] op_sel_hi:[0,1,1]
	v_pk_fma_f32 v[4:5], v[6:7], v[102:103], v[4:5] op_sel_hi:[0,1,1]
	v_pk_add_f32 v[8:9], v[8:9], v[36:37]
	v_mov_b32_e32 v29, v32
	v_mov_b32_e32 v104, v98
	v_mov_b32_e32 v105, v114
	v_mul_f32_e32 v34, v7, v137
	v_mov_b32_e32 v35, v33
	v_pk_mul_f32 v[30:31], v[0:1], v[146:147]
	v_pk_fma_f32 v[10:11], v[6:7], v[60:61], v[10:11] op_sel:[1,0,0]
	v_pk_fma_f32 v[12:13], v[6:7], v[88:89], v[12:13] op_sel:[1,0,0]
	v_pk_fma_f32 v[4:5], v[6:7], v[120:121], v[4:5] op_sel:[1,0,0]
	v_pk_add_f32 v[6:7], v[8:9], v[28:29]
	v_mov_b32_e32 v114, v99
	v_mul_f32_e32 v14, v0, v130
	v_pk_fma_f32 v[8:9], v[0:1], v[48:49], v[10:11] op_sel_hi:[0,1,1]
	v_pk_fma_f32 v[10:11], v[0:1], v[76:77], v[12:13] op_sel_hi:[0,1,1]
	v_pk_fma_f32 v[4:5], v[0:1], v[104:105], v[4:5] op_sel_hi:[0,1,1]
	v_pk_add_f32 v[6:7], v[6:7], v[34:35]
	v_mov_b32_e32 v15, v30
	v_pk_mul_f32 v[78:79], v[2:3], v[148:149]
	v_mov_b32_e32 v98, v100
	v_mov_b32_e32 v99, v116
	v_mul_f32_e32 v32, v1, v131
	v_mov_b32_e32 v33, v31
	v_pk_fma_f32 v[8:9], v[0:1], v[16:17], v[8:9] op_sel:[1,0,0]
	v_pk_fma_f32 v[10:11], v[0:1], v[20:21], v[10:11] op_sel:[1,0,0]
	v_pk_fma_f32 v[0:1], v[0:1], v[114:115], v[4:5] op_sel:[1,0,0]
	v_pk_add_f32 v[4:5], v[6:7], v[14:15]
	v_mov_b32_e32 v116, v101
	v_mov_b32_e32 v51, v78
	v_pk_fma_f32 v[0:1], v[2:3], v[98:99], v[0:1] op_sel_hi:[0,1,1]
	v_pk_add_f32 v[4:5], v[4:5], v[32:33]
	v_mul_f32_e32 v100, v3, v133
	v_mov_b32_e32 v101, v79
	v_pk_fma_f32 v[6:7], v[2:3], v[42:43], v[8:9] op_sel_hi:[0,1,1]
	v_pk_fma_f32 v[8:9], v[2:3], v[70:71], v[10:11] op_sel_hi:[0,1,1]
	v_pk_fma_f32 v[30:31], v[2:3], v[116:117], v[0:1] op_sel:[1,0,0]
	v_pk_add_f32 v[0:1], v[4:5], v[50:51]
	v_lshl_add_u64 v[26:27], v[26:27], 0, s[2:3]
	v_pk_fma_f32 v[34:35], v[2:3], v[18:19], v[6:7] op_sel:[1,0,0]
	v_pk_fma_f32 v[32:33], v[2:3], v[22:23], v[8:9] op_sel:[1,0,0]
	v_pk_add_f32 v[28:29], v[0:1], v[100:101]
	s_cbranch_scc1 .LBB0_511
	s_lshl_b32 s4, s9, 6
	s_and_b32 s4, s4, 0x3c0
	v_or_b32_e32 v4, s4, v41
	v_lshlrev_b32_e32 v24, 11, v4
	v_lshl_add_u64 v[4:5], s[0:1], 0, v[24:25]
	v_lshl_add_u64 v[4:5], s[22:23], 1, v[4:5]
	s_and_b32 s4, s9, 0xf0
	s_add_i32 s9, s9, s12
	s_add_i32 s15, s15, s16
	v_lshl_add_u64 v[4:5], v[4:5], 0, s[4:5]
	s_cmpk_gt_i32 s9, 0x3ff
	v_cvt_pk_bf16_f32 v0, v34, v35
	v_cvt_pk_bf16_f32 v1, v32, v33
	v_cvt_pk_bf16_f32 v2, v30, v31
	v_cvt_pk_bf16_f32 v3, v28, v29
	global_store_dwordx4 v[4:5], v[0:3], off
	s_cbranch_scc0 .LBB0_510
